# scan: state-update LDS reads (kd fragments and decay vectors) issued early beside the decay prep instead of just before each state MFMA
# baseline (speedup 1.0000x reference)
; #define LAS __attribute__((address_space(3)))
; #define SC_LOAD(c_) do { const bf16* rp_ = proj + (size_t)scan_row16(b, dir, (c_), st) * HIN + h * 128 + sc8 * 8; \
;         rq = *(const u32x4*)rp_; rk = *(const u32x4*)(rp_ + kcol - h * 128); rv = *(const u32x4*)(rp_ + 3072); } while (0)
; __device__ __forceinline__ void scan_phase(LAS unsigned char* lds, bf16* proj, int G, int bid) {
;     ...
;         __syncthreads();
;         {
;             const u32x4 z4 = (u32x4){0u, 0u, 0u, 0u};
;             for (int o_ = tid * 16; o_ < 8192; o_ += NTHR * 16) { *(LAS u32x4*)(lds + O_KD + o_) = z4; *(LAS u32x4*)(lds + SET + O_KD + o_) = z4; *(LAS u32x4*)(lds + O_VT + o_) = z4; *(LAS u32x4*)(lds + O_VT + 8192 + o_) = z4; *(LAS u32x4*)(lds + O_VT + 16384 + o_) = z4; }
;         }
;         if (stager) SC_LOAD(0);
;         __syncthreads();
;         if (stager) { SC_WRITE(0); SC_LOAD(1); }
;         __syncthreads();
;         SC_PREP(0);
;         if (stager) { SC_WRITE(1); SC_LOAD(2); }
;         __syncthreads();
; #pragma unroll 1
;         for (int c = 0; c < 272; ++c) {
;             LAS unsigned char* set = lds + (c & 1) * SET;
;             SC_PREP(c + 1);
;             {
;                 const LAS unsigned char* qeb = set + O_QE + fr * QST; const LAS unsigned char* keb = set + O_KE + fr * QST;
;                 bf16x8 kaf[4], qbf[4];
; #pragma unroll
;                 for (int i = 0; i < 4; ++i) { kaf[i] = *(const LAS bf16x8*)(keb + (32 * i + fq * 8) * 2); qbf[i] = *(const LAS bf16x8*)(qeb + (32 * i + fq * 8) * 2); }
;                 u32x2 qlo[4], qhi[4];
; #pragma unroll
;                 for (int i = 0; i < 4; ++i) { qlo[i] = *(const LAS u32x2*)(qeb + (32 * i + fq * 4) * 2); qhi[i] = *(const LAS u32x2*)(qeb + (32 * i + 16 + fq * 4) * 2); }
;                 const bf16x8 vf = *(const LAS bf16x8*)(lds + O_VT + (c % 3) * 8192 + (wave * 16 + fr) * 64 + fq * 16);
.LBB0_433:
	s_add_i32 s7, s6, 1
	s_bitcmp1_b32 s7, 0
	s_cselect_b32 s0, 0x8600, 0
	s_add_i32 s0, s0, 0
	v_lshl_add_u32 v1, v80, 2, s0
	v_lshl_add_u32 v0, v71, 2, v1
	ds_read2_b32 v[48:49], v0 offset1:132
	v_add_u32_e32 v3, 0x2000, v0
	ds_read2_b32 v[50:51], v3 offset0:64 offset1:196
	v_add_u32_e32 v3, 0x400, v0
	ds_read2_b32 v[98:99], v3 offset0:8 offset1:140
	v_add_u32_e32 v0, 0x2400, v0
	ds_read2_b32 v[100:101], v0 offset0:72 offset1:204
	s_bitcmp1_b32 s6, 0
	s_cselect_b32 s101, 0x8600, 0
	v_add_u32_e32 v182, s101, v89
	v_add_u32_e32 v183, v182, v57
	ds_read_b128 v[184:187], v183 offset:25600
	ds_read_b128 v[236:239], v182 offset:33792
	ds_read_b128 v[240:243], v182 offset:33856
	ds_read_b128 v[188:191], v183 offset:26624
	ds_read_b128 v[192:195], v183 offset:27648
	ds_read_b128 v[244:247], v182 offset:33920
	ds_read_b128 v[248:251], v182 offset:33984
	ds_read_b128 v[196:199], v183 offset:28672
	ds_read_b128 v[200:203], v183 offset:29696
	ds_read_b128 v[168:171], v182 offset:34048
	ds_read_b128 v[224:227], v183 offset:30720
	s_waitcnt lgkmcnt(14)
	v_sub_f32_e32 v0, 1.0, v48
	v_max_f32_e32 v3, 0x3bdb8bac, v0
	v_sub_f32_e32 v0, 1.0, v49
	v_max_f32_e32 v0, 0x3bdb8bac, v0
	v_mul_f32_e32 v65, v3, v0
	s_waitcnt lgkmcnt(12)
	v_sub_f32_e32 v0, 1.0, v98
	v_max_f32_e32 v0, 0x3bdb8bac, v0
	v_mul_f32_e32 v104, v65, v0
	v_sub_f32_e32 v0, 1.0, v99
	v_max_f32_e32 v0, 0x3bdb8bac, v0
	v_mul_f32_e32 v105, v104, v0
	v_add3_u32 v1, v1, v90, v72
	s_nop 0
	v_mul_f32_dpp v0, v105, v105 quad_perm:[0,0,1,2] row_mask:0xf bank_mask:0xf bound_ctrl:1
	v_cndmask_b32_e64 v0, v0, v105, s[44:45]
	s_nop 1
	v_mul_f32_dpp v102, v0, v0 quad_perm:[0,0,0,1] row_mask:0xf bank_mask:0xf bound_ctrl:1
	v_cndmask_b32_e64 v102, v0, v102, s[46:47]
	v_mov_b32_e32 v0, 0
	s_nop 1
	v_mov_b32_dpp v0, v102 quad_perm:[0,0,1,2] row_mask:0xf bank_mask:0xf
	v_cndmask_b32_e64 v106, v0, 1.0, s[44:45]
	v_mov_b32_e32 v0, 0
	v_mul_f32_e32 v3, v3, v106
	s_nop 0
	v_mov_b32_dpp v0, v102 quad_perm:[3,3,3,3] row_mask:0xf bank_mask:0xf
	v_rcp_f32_e32 v102, v3
	v_mul_f32_e32 v3, v50, v3
	v_cvt_pk_bf16_f32 v3, v3, s0
	ds_write_b16 v1, v3 offset:16896
	v_mul_f32_e32 v3, v65, v106
	v_rcp_f32_e32 v103, v3
	v_mul_f32_e32 v3, v51, v3
	v_cvt_pk_bf16_f32 v3, v3, s0
	ds_write_b16 v1, v3 offset:17168
	v_mul_f32_e32 v3, v104, v106
	v_rcp_f32_e32 v50, v3
	s_waitcnt lgkmcnt(13)
	ds_read_b128 v[172:175], v182 offset:34112
	ds_read_b128 v[176:179], v182 offset:34176
	ds_read_b128 v[214:217], v182 offset:34240
	ds_read_b128 v[228:231], v183 offset:31744
	ds_read_b128 v[232:235], v183 offset:32768
	v_mul_f32_e32 v3, v100, v3
	v_cvt_pk_bf16_f32 v3, v3, s0
	ds_write_b16 v1, v3 offset:17440
	v_mul_f32_e32 v3, v105, v106
	v_rcp_f32_e32 v51, v3
	v_mul_f32_e32 v3, v101, v3
	v_cvt_pk_bf16_f32 v3, v3, s0
	v_pk_mul_f32 v[48:49], v[48:49], v[102:103]
	ds_write_b16 v1, v3 offset:17712
	v_cvt_pk_bf16_f32 v3, v48, s0
	ds_write_b16 v1, v3 offset:21248
	v_cvt_pk_bf16_f32 v3, v49, s0
	v_pk_mul_f32 v[50:51], v[98:99], v[50:51]
	ds_write_b16 v1, v3 offset:21520
	v_cvt_pk_bf16_f32 v3, v50, s0
	ds_write_b16 v1, v3 offset:21792
	v_cvt_pk_bf16_f32 v3, v51, s0
	v_pk_mul_f32 v[100:101], v[48:49], v[0:1] op_sel_hi:[1,0]
	v_pk_mul_f32 v[98:99], v[50:51], v[0:1] op_sel_hi:[1,0]
	ds_write_b16 v1, v3 offset:22064
	v_add_u32_e32 v1, s0, v83
	v_cvt_pk_bf16_f32 v48, v100, v101
	v_cvt_pk_bf16_f32 v49, v98, v99
	v_add_u32_e32 v3, v1, v55
	ds_write_b64 v3, v[48:49] offset:25600
	s_and_saveexec_b64 s[0:1], s[44:45]
	v_add_u32_e32 v1, v1, v84
	ds_write_b32 v1, v0 offset:33792
	s_or_b64 exec, exec, s[0:1]
	s_mul_hi_u32 s0, s6, 0xaaaaaaab
	s_lshr_b32 s0, s0, 1
	s_bitcmp1_b32 s6, 0
	s_cselect_b32 s1, 0x8600, 0
	s_add_i32 s14, s1, 0
	v_add_u32_e32 v0, s14, v88
	v_add_u32_e32 v1, v0, v89
	ds_read_b128 v[48:51], v1 offset:21248
	ds_read_b128 v[98:101], v1 offset:21312
	ds_read_b128 v[102:105], v1 offset:16896
	ds_read_b128 v[106:109], v1 offset:16960
	ds_read_b128 v[110:113], v1 offset:21376
	ds_read_b128 v[114:117], v1 offset:21440
	ds_read_b128 v[118:121], v1 offset:17024
	ds_read_b128 v[122:125], v1 offset:17088
	v_add_u32_e32 v0, v0, v56
	v_add_u32_e32 v0, 0x4000, v0
	ds_read2_b64 v[126:129], v0 offset0:64 offset1:68
	ds_read2_b64 v[130:133], v0 offset0:72 offset1:76
	ds_read2_b64 v[134:137], v0 offset0:80 offset1:84
	ds_read2_b64 v[138:141], v0 offset0:88 offset1:92
	s_mulk_i32 s0, 0xa000
	v_add_u32_e32 v0, s0, v95
	ds_read_b128 v[142:145], v0
	s_setprio 1
	s_waitcnt lgkmcnt(10)
; #define LAS __attribute__((address_space(3)))
; __device__ __forceinline__ void scan_phase(LAS unsigned char* lds, bf16* proj, int G, int bid) {
;     ...
;                 const LAS unsigned char* qeb = set + O_QE + fr * QST; const LAS unsigned char* keb = set + O_KE + fr * QST;
;                 bf16x8 kaf[4], qbf[4];
; #pragma unroll
;                 for (int i = 0; i < 4; ++i) { kaf[i] = *(const LAS bf16x8*)(keb + (32 * i + fq * 8) * 2); qbf[i] = *(const LAS bf16x8*)(qeb + (32 * i + fq * 8) * 2); }
;                 u32x2 qlo[4], qhi[4];
; #pragma unroll
;                 for (int i = 0; i < 4; ++i) { qlo[i] = *(const LAS u32x2*)(qeb + (32 * i + fq * 4) * 2); qhi[i] = *(const LAS u32x2*)(qeb + (32 * i + 16 + fq * 4) * 2); }
;                 const bf16x8 vf = *(const LAS bf16x8*)(lds + O_VT + (c % 3) * 8192 + (wave * 16 + fr) * 64 + fq * 16);
;                 f32x4 pt = (f32x4){0.f, 0.f, 0.f, 0.f};
;                 __builtin_amdgcn_s_setprio(1);
; #pragma unroll
;                 for (int i = 0; i < 4; ++i) pt = __builtin_amdgcn_mfma_f32_16x16x32_bf16(kaf[i], qbf[i], pt, 0, 0, 0);
;                 f32x4 oacc = (f32x4){0.f, 0.f, 0.f, 0.f};
; #pragma unroll
;                 for (int i = 0; i < 4; ++i) {
;                     u32x4 sw; sw.x = cvt_pk_bf16(S[2 * i][0], S[2 * i][1]); sw.y = cvt_pk_bf16(S[2 * i][2], S[2 * i][3]); sw.z = cvt_pk_bf16(S[2 * i + 1][0], S[2 * i + 1][1]); sw.w = cvt_pk_bf16(S[2 * i + 1][2], S[2 * i + 1][3]);
;                     u32x4 qw; qw.x = qlo[i][0]; qw.y = qlo[i][1]; qw.z = qhi[i][0]; qw.w = qhi[i][1];
;                     oacc = __builtin_amdgcn_mfma_f32_16x16x32_bf16(__builtin_bit_cast(bf16x8, sw), __builtin_bit_cast(bf16x8, qw), oacc, 0, 0, 0);
;                 }
;                 const LAS float* dv = (const LAS float*)(set + O_DV);
; #pragma unroll
;                 for (int kt = 0; kt < 8; ++kt) {
;                     const f32x4 d4 = *(const LAS f32x4*)(dv + kt * 16 + fq * 4);
;                     const bf16x8 ka = *(const LAS bf16x8*)(set + O_KD + (kt * 16 + fr) * 64 + fq * 16);
;                     S[kt] = __builtin_amdgcn_mfma_f32_16x16x32_bf16(ka, vf, S[kt] * d4, 0, 0, 0);
;                 }
; #pragma unroll
;                 for (int j = 0; j < 4; ++j) pt[j] = (fq * 4 + j <= fr) ? pt[j] : 0.f;
;                 u32x4 pw; pw.x = cvt_pk_bf16(pt[0], pt[1]); pw.y = cvt_pk_bf16(pt[2], pt[3]); pw.z = 0u; pw.w = 0u;
	v_mfma_f32_16x16x32_bf16 v[48:51], v[48:51], v[102:105], 0
	v_add_u32_e32 v0, s14, v89
	v_add_u32_e32 v1, v0, v57
	v_cvt_pk_bf16_f32 v146, v44, v45
	s_waitcnt lgkmcnt(9)
	v_mfma_f32_16x16x32_bf16 v[48:51], v[98:101], v[106:109], v[48:51]
	v_cvt_pk_bf16_f32 v147, v46, v47
	v_cvt_pk_bf16_f32 v148, v16, v17
	s_waitcnt lgkmcnt(6)
	v_mfma_f32_16x16x32_bf16 v[48:51], v[110:113], v[118:121], v[48:51]
	s_waitcnt lgkmcnt(0)
	v_pk_mul_f32 v[46:47], v[46:47], v[238:239]
	v_pk_mul_f32 v[44:45], v[44:45], v[236:237]
	v_pk_mul_f32 v[16:17], v[16:17], v[240:241]
	v_cvt_pk_bf16_f32 v149, v18, v19
	v_mfma_f32_16x16x32_bf16 v[44:47], v[184:187], v[142:145], v[44:47]
	v_cvt_pk_bf16_f32 v150, v20, v21
	v_cvt_pk_bf16_f32 v151, v22, v23
	v_pk_mul_f32 v[18:19], v[18:19], v[242:243]
	v_pk_mul_f32 v[22:23], v[22:23], v[246:247]
	v_pk_mul_f32 v[20:21], v[20:21], v[244:245]
	v_mfma_f32_16x16x32_bf16 v[16:19], v[188:191], v[142:145], v[16:19]
	v_cvt_pk_bf16_f32 v152, v24, v25
	v_cvt_pk_bf16_f32 v153, v26, v27
	v_mfma_f32_16x16x32_bf16 v[20:23], v[192:195], v[142:145], v[20:23]
	v_pk_mul_f32 v[26:27], v[26:27], v[250:251]
	v_pk_mul_f32 v[24:25], v[24:25], v[248:249]
	v_cvt_pk_bf16_f32 v154, v28, v29
	v_cvt_pk_bf16_f32 v155, v30, v31
	v_mfma_f32_16x16x32_bf16 v[24:27], v[196:199], v[142:145], v[24:27]
	v_pk_mul_f32 v[30:31], v[30:31], v[170:171]
	v_pk_mul_f32 v[28:29], v[28:29], v[168:169]
	v_cvt_pk_bf16_f32 v156, v32, v33
	v_cvt_pk_bf16_f32 v157, v34, v35
	v_mfma_f32_16x16x32_bf16 v[28:31], v[200:203], v[142:145], v[28:31]
	v_pk_mul_f32 v[34:35], v[34:35], v[174:175]
	v_pk_mul_f32 v[32:33], v[32:33], v[172:173]
	v_cvt_pk_bf16_f32 v102, v36, v37
	v_cvt_pk_bf16_f32 v103, v38, v39
	v_mfma_f32_16x16x32_bf16 v[32:35], v[224:227], v[142:145], v[32:35]
	v_pk_mul_f32 v[38:39], v[38:39], v[178:179]
	v_pk_mul_f32 v[36:37], v[36:37], v[176:177]
	v_mfma_f32_16x16x32_bf16 v[98:101], v[146:149], v[126:129], 0
	v_cvt_pk_bf16_f32 v104, v40, v41
	v_cvt_pk_bf16_f32 v105, v42, v43
	v_mfma_f32_16x16x32_bf16 v[98:101], v[150:153], v[130:133], v[98:101]
	v_pk_mul_f32 v[42:43], v[42:43], v[216:217]
	v_pk_mul_f32 v[40:41], v[40:41], v[214:215]
	v_mfma_f32_16x16x32_bf16 v[48:51], v[114:117], v[122:125], v[48:51]
	v_mfma_f32_16x16x32_bf16 v[98:101], v[154:157], v[134:137], v[98:101]
	v_mfma_f32_16x16x32_bf16 v[98:101], v[102:105], v[138:141], v[98:101]
	s_nop 5
	v_cvt_pk_bf16_f32 v0, v48, s0
	v_cvt_pk_bf16_f32 v1, v49, s0
	v_cndmask_b32_e64 v0, v0, 0, s[48:49]
	v_cndmask_b32_e64 v1, 0, v1, s[50:51]
	v_perm_b32 v0, v1, v0, s11
	v_cvt_pk_bf16_f32 v1, v50, s0
	v_cvt_pk_bf16_f32 v3, v51, s0
	v_cndmask_b32_e64 v1, v1, 0, s[52:53]
	v_cndmask_b32_e64 v3, v3, 0, s[54:55]
	v_perm_b32 v1, v3, v1, s11
	v_mov_b32_e32 v3, v2
	v_mfma_f32_16x16x32_bf16 v[36:39], v[228:231], v[142:145], v[36:39]
	v_mfma_f32_16x16x32_bf16 v[40:43], v[232:235], v[142:145], v[40:43]
	v_mfma_f32_16x16x32_bf16 v[48:51], v[142:145], v[0:3], v[98:101]
	s_setprio 0
	s_mov_b64 s[0:1], -1
	s_cmp_gt_u32 s6, 15
	v_add_u32_e32 v1, s4, v53
	s_cbranch_scc0 .LBB0_437
	v_add_u32_e32 v0, 0xffffff00, v1
	v_cndmask_b32_e64 v0, v96, v0, s[56:57]
	v_add_u32_e32 v0, s5, v0
	s_mov_b64 s[0:1], 0
